# nt hint on the 16 single-use dwordx4 loads of the final RMSNorm-residual phase
# speedup vs baseline: 1.0091x; 1.0091x over previous
; __device__ __forceinline__ float bf_lo(unsigned w) { return __uint_as_float(w << 16); }
; __device__ __forceinline__ float bf_hi(unsigned w) { return __uint_as_float(w & 0xffff0000u); }
; __global__ void __launch_bounds__(NWAVES * 64, 2) hymba_fwd(Args a) {
;     ...
;         for (int it = 0; it < 4; ++it) { const int mb = team_pm * 256 + team_k * 64 + wave * 8 + it * 2;
;             v4u fv[2][4], hv[2][4]; float sf[2], rhi[2];
; #pragma unroll
;             for (int q = 0; q < 2; ++q) { const v4u* fr = (const v4u*)(MIX + (size_t)(mb + q) * DM); const v4u* hr = (const v4u*)(R1 + (size_t)(mb + q) * DM); rhi[q] = ((const float*)(ws + WS_RH))[mb + q];
; #pragma unroll
;                 for (int j = 0; j < 4; ++j) { fv[q][j] = fr[64 * j + lane]; hv[q][j] = hr[64 * j + lane]; } }
; #pragma unroll
;             for (int q = 0; q < 2; ++q) { float t = 0.f;
; #pragma unroll
;                 for (int j = 0; j < 4; ++j)
; #pragma unroll
;                     for (int e = 0; e < 4; ++e) { const float f0 = bf_lo(fv[q][j][e]), f1 = bf_hi(fv[q][j][e]); t += f0 * f0 + f1 * f1; }
;                 sf[q] = t; }
.LBB0_975:
	v_lshl_add_u64 v[38:39], s[94:95], 0, v[0:1]
	v_add_co_u32_e32 v48, vcc, 0xb000000, v38
	s_add_u32 s2, s94, s4
	s_nop 0
	v_addc_co_u32_e32 v49, vcc, 0, v39, vcc
	v_add_co_u32_e32 v54, vcc, 0x7000000, v38
	s_addc_u32 s3, s95, s5
	s_nop 0
	v_addc_co_u32_e32 v55, vcc, 0, v39, vcc
	global_load_dwordx2 v[44:45], v126, s[2:3]
	global_load_dwordx4 v[50:53], v[48:49], off nt
	global_load_dwordx4 v[58:61], v[48:49], off offset:1024 nt
	global_load_dwordx4 v[64:67], v[48:49], off offset:2048 nt
	v_add_co_u32_e32 v56, vcc, s11, v38
	global_load_dwordx4 v[74:77], v[48:49], off offset:3072 nt
	global_load_dwordx4 v[78:81], v[54:55], off nt
	global_load_dwordx4 v[82:85], v[54:55], off offset:1024 nt
	global_load_dwordx4 v[90:93], v[54:55], off offset:2048 nt
	v_addc_co_u32_e32 v57, vcc, 0, v39, vcc
	global_load_dwordx4 v[98:101], v[54:55], off offset:3072 nt
	global_load_dwordx4 v[112:115], v[56:57], off nt
	global_load_dwordx4 v[120:123], v[56:57], off offset:1024 nt
	global_load_dwordx4 v[130:133], v[56:57], off offset:2048 nt
	v_add_co_u32_e32 v38, vcc, s12, v38
	v_lshl_add_u64 v[36:37], v[34:35], 0, s[6:7]
	s_nop 0
	v_addc_co_u32_e32 v39, vcc, 0, v39, vcc
	global_load_dwordx4 v[134:137], v[38:39], off offset:1024 nt
	global_load_dwordx4 v[138:141], v[38:39], off offset:2048 nt
	global_load_dwordx4 v[142:145], v[38:39], off nt
	global_load_dwordx4 v[154:157], v[56:57], off offset:3072 nt
	global_load_dwordx4 v[158:161], v[38:39], off offset:3072 nt
	v_add_co_u32_e64 v46, s[0:1], s10, v36
	s_add_u32 s6, s6, 0x4000
	s_nop 0
	v_addc_co_u32_e64 v47, s[0:1], 0, v37, s[0:1]
	v_add_co_u32_e64 v42, s[0:1], s14, v36
	s_addc_u32 s7, s7, 0
	s_nop 0
	v_addc_co_u32_e64 v43, s[0:1], 0, v37, s[0:1]
	v_add_co_u32_e64 v40, s[0:1], s15, v36
	s_add_u32 s4, s4, 8
	s_nop 0
	v_addc_co_u32_e64 v41, s[0:1], 0, v37, s[0:1]
	s_addc_u32 s5, s5, 0
	v_lshl_add_u64 v[0:1], v[0:1], 0, s[8:9]
	s_cmp_eq_u32 s6, 0x10000
	s_waitcnt vmcnt(15)
	v_and_b32_e32 v39, 0xffff0000, v50
	v_and_b32_e32 v49, 0xffff0000, v51
	v_lshlrev_b32_e32 v38, 16, v50
	v_lshlrev_b32_e32 v48, 16, v51
	v_and_b32_e32 v51, 0xffff0000, v52
	v_mul_f32_e32 v129, v39, v39
	v_mul_f32_e32 v153, v49, v49
	v_lshlrev_b32_e32 v50, 16, v52
	v_lshlrev_b32_e32 v52, 16, v53
	v_and_b32_e32 v53, 0xffff0000, v53
	v_mul_f32_e32 v173, v51, v51
	v_fmac_f32_e32 v129, v38, v38
	v_fmac_f32_e32 v153, v48, v48
	s_waitcnt vmcnt(14)
	v_and_b32_e32 v55, 0xffff0000, v58
	v_mul_f32_e32 v192, v53, v53
	v_fmac_f32_e32 v173, v50, v50
	s_waitcnt vmcnt(7)
	v_and_b32_e32 v109, 0xffff0000, v112
	v_and_b32_e32 v111, 0xffff0000, v113
	v_add_f32_e32 v129, v129, v153
	v_lshlrev_b32_e32 v54, 16, v58
	v_and_b32_e32 v57, 0xffff0000, v59
	v_mul_f32_e32 v193, v55, v55
	v_fmac_f32_e32 v192, v52, v52
	v_lshlrev_b32_e32 v108, 16, v112
	v_lshlrev_b32_e32 v110, 16, v113
	v_and_b32_e32 v113, 0xffff0000, v114
	v_mul_f32_e32 v153, v109, v109
	v_mul_f32_e32 v203, v111, v111
	v_add_f32_e32 v129, v129, v173
	v_lshlrev_b32_e32 v56, 16, v59
	v_and_b32_e32 v59, 0xffff0000, v60
	v_mul_f32_e32 v194, v57, v57
	v_fmac_f32_e32 v193, v54, v54
	v_lshlrev_b32_e32 v112, 16, v114
	v_lshlrev_b32_e32 v114, 16, v115
	v_and_b32_e32 v115, 0xffff0000, v115
	v_mul_f32_e32 v204, v113, v113
	v_fmac_f32_e32 v153, v108, v108
	v_fmac_f32_e32 v203, v110, v110
	v_add_f32_e32 v129, v129, v192
	v_lshlrev_b32_e32 v58, 16, v60
	v_lshlrev_b32_e32 v60, 16, v61
	v_and_b32_e32 v61, 0xffff0000, v61
	v_mul_f32_e32 v195, v59, v59
	v_fmac_f32_e32 v194, v56, v56
	s_waitcnt vmcnt(6)
	v_and_b32_e32 v117, 0xffff0000, v120
	v_mul_f32_e32 v205, v115, v115
	v_fmac_f32_e32 v204, v112, v112
	v_add_f32_e32 v153, v153, v203
	v_add_f32_e32 v129, v129, v193
	v_and_b32_e32 v63, 0xffff0000, v64
	v_mul_f32_e32 v196, v61, v61
	v_fmac_f32_e32 v195, v58, v58
	v_lshlrev_b32_e32 v116, 16, v120
	v_and_b32_e32 v119, 0xffff0000, v121
	v_mul_f32_e32 v206, v117, v117
	v_fmac_f32_e32 v205, v114, v114
	v_add_f32_e32 v153, v153, v204
	v_add_f32_e32 v129, v129, v194
	v_lshlrev_b32_e32 v62, 16, v64
	v_lshlrev_b32_e32 v64, 16, v65
	v_and_b32_e32 v65, 0xffff0000, v65
	v_mul_f32_e32 v197, v63, v63
	v_fmac_f32_e32 v196, v60, v60
	v_lshlrev_b32_e32 v118, 16, v121
	v_and_b32_e32 v121, 0xffff0000, v122
	v_mul_f32_e32 v207, v119, v119
	v_fmac_f32_e32 v206, v116, v116
	v_add_f32_e32 v153, v153, v205
	v_add_f32_e32 v129, v129, v195
	v_and_b32_e32 v69, 0xffff0000, v66
	v_mul_f32_e32 v198, v65, v65
	v_fmac_f32_e32 v197, v62, v62
	v_lshlrev_b32_e32 v120, 16, v122
	v_lshlrev_b32_e32 v122, 16, v123
	v_and_b32_e32 v123, 0xffff0000, v123
	v_mul_f32_e32 v208, v121, v121
	v_fmac_f32_e32 v207, v118, v118
	v_add_f32_e32 v153, v153, v206
	v_add_f32_e32 v129, v129, v196
	v_lshlrev_b32_e32 v68, 16, v66
	v_and_b32_e32 v73, 0xffff0000, v67
	v_mul_f32_e32 v199, v69, v69
	v_fmac_f32_e32 v198, v64, v64
	s_waitcnt vmcnt(5)
	v_and_b32_e32 v125, 0xffff0000, v130
	v_mul_f32_e32 v209, v123, v123
	v_fmac_f32_e32 v208, v120, v120
	v_add_f32_e32 v153, v153, v207
	v_add_f32_e32 v129, v129, v197
	v_lshlrev_b32_e32 v72, 16, v67
	v_mul_f32_e32 v200, v73, v73
	v_and_b32_e32 v103, 0xffff0000, v74
	v_fmac_f32_e32 v199, v68, v68
	v_lshlrev_b32_e32 v124, 16, v130
	v_lshlrev_b32_e32 v130, 16, v131
	v_and_b32_e32 v131, 0xffff0000, v131
	v_mul_f32_e32 v210, v125, v125
	v_fmac_f32_e32 v209, v122, v122
	v_add_f32_e32 v153, v153, v208
	v_add_f32_e32 v129, v129, v198
	v_lshlrev_b32_e32 v102, 16, v74
	v_and_b32_e32 v105, 0xffff0000, v75
	v_and_b32_e32 v107, 0xffff0000, v77
	v_and_b32_e32 v106, 0xffff0000, v76
	v_fmac_f32_e32 v200, v72, v72
	v_mul_f32_e32 v201, v103, v103
	v_and_b32_e32 v165, 0xffff0000, v132
	v_mul_f32_e32 v211, v131, v131
	v_fmac_f32_e32 v210, v124, v124
	v_add_f32_e32 v153, v153, v209
	v_add_f32_e32 v129, v129, v199
	v_lshlrev_b32_e32 v104, 16, v75
	v_lshlrev_b32_e32 v147, 16, v77
	v_lshlrev_b32_e32 v146, 16, v76
	v_mul_f32_e32 v202, v105, v105
	v_pk_mul_f32 v[162:163], v[106:107], v[106:107]
	v_lshlrev_b32_e32 v164, 16, v132
	v_lshlrev_b32_e32 v132, 16, v133
	v_and_b32_e32 v133, 0xffff0000, v133
	v_fmac_f32_e32 v201, v102, v102
	v_mul_f32_e32 v212, v165, v165
	v_fmac_f32_e32 v211, v130, v130
	v_add_f32_e32 v153, v153, v210
	v_add_f32_e32 v129, v129, v200
	v_mov_b32_e32 v166, v146
	v_mov_b32_e32 v167, v106
	v_mov_b32_e32 v106, v147
	v_fmac_f32_e32 v202, v104, v104
	v_pk_fma_f32 v[146:147], v[146:147], v[146:147], v[162:163]
	v_mul_f32_e32 v213, v133, v133
	s_waitcnt vmcnt(1)
; __device__ __forceinline__ float bf_lo(unsigned w) { return __uint_as_float(w << 16); }
; __device__ __forceinline__ float bf_hi(unsigned w) { return __uint_as_float(w & 0xffff0000u); }
; __device__ __forceinline__ float wave_sum(float v) {
; #pragma unroll
;     for (int o = 1; o < 64; o <<= 1) v += __shfl_xor(v, o);
;     return v;
; __global__ void __launch_bounds__(NWAVES * 64, 2) hymba_fwd(Args a) {
;     ...
;             for (int q = 0; q < 2; ++q) { float t = 0.f;
; #pragma unroll
;                 for (int j = 0; j < 4; ++j)
; #pragma unroll
;                     for (int e = 0; e < 4; ++e) { const float f0 = bf_lo(fv[q][j][e]), f1 = bf_hi(fv[q][j][e]); t += f0 * f0 + f1 * f1; }
;                 sf[q] = t; }
; #pragma unroll
;             for (int q = 0; q < 2; ++q) {
;                 const float rf = 1.0f / sqrtf(wave_sum(sf[q]) * (1.0f / DM) + RMS_EPS), rx = rhi[q]; f32x4* ho = (f32x4*)(a.out + (size_t)(mb + q) * DM);
	v_and_b32_e32 v163, 0xffff0000, v154
	v_fmac_f32_e32 v212, v164, v164
	v_add_f32_e32 v153, v153, v211
	v_add_f32_e32 v129, v129, v201
	v_lshlrev_b32_e32 v162, 16, v154
	v_lshlrev_b32_e32 v154, 16, v155
	v_and_b32_e32 v155, 0xffff0000, v155
	v_fmac_f32_e32 v213, v132, v132
	v_mul_f32_e32 v173, v163, v163
	v_add_f32_e32 v153, v153, v212
	v_add_f32_e32 v129, v129, v202
	v_lshlrev_b32_e32 v169, 16, v157
	v_lshlrev_b32_e32 v168, 16, v156
	v_and_b32_e32 v157, 0xffff0000, v157
	v_and_b32_e32 v156, 0xffff0000, v156
	v_mul_f32_e32 v214, v155, v155
	v_fmac_f32_e32 v173, v162, v162
	v_add_f32_e32 v153, v153, v213
	v_add_f32_e32 v129, v129, v146
	v_pk_mul_f32 v[188:189], v[156:157], v[156:157]
	v_fmac_f32_e32 v214, v154, v154
	v_add_f32_e32 v146, v153, v173
	v_add_f32_e32 v129, v129, v147
	v_mov_b32_e32 v190, v168
	v_mov_b32_e32 v191, v156
	v_mov_b32_e32 v156, v169
	v_pk_fma_f32 v[168:169], v[168:169], v[168:169], v[188:189]
	v_add_f32_e32 v146, v146, v214
	ds_bpermute_b32 v147, v148, v129
	v_add_f32_e32 v146, v146, v168
	v_add_f32_e32 v146, v146, v169
	ds_bpermute_b32 v153, v148, v146
	v_lshlrev_b32_e32 v66, 16, v78
	s_waitcnt lgkmcnt(1)
	v_add_f32_e32 v129, v129, v147
	ds_bpermute_b32 v147, v149, v129
	v_and_b32_e32 v67, 0xffff0000, v78
	s_waitcnt lgkmcnt(1)
	v_add_f32_e32 v146, v146, v153
	ds_bpermute_b32 v153, v149, v146
	v_lshlrev_b32_e32 v70, 16, v79
	s_waitcnt lgkmcnt(1)
	v_add_f32_e32 v129, v129, v147
	ds_bpermute_b32 v147, v150, v129
	v_and_b32_e32 v71, 0xffff0000, v79
	s_waitcnt lgkmcnt(1)
	v_add_f32_e32 v146, v146, v153
	ds_bpermute_b32 v153, v150, v146
	v_lshlrev_b32_e32 v74, 16, v80
	s_waitcnt lgkmcnt(1)
	v_add_f32_e32 v129, v129, v147
	ds_bpermute_b32 v147, v151, v129
	v_and_b32_e32 v75, 0xffff0000, v80
	s_waitcnt lgkmcnt(1)
	v_add_f32_e32 v146, v146, v153
	ds_bpermute_b32 v153, v151, v146
	v_lshlrev_b32_e32 v76, 16, v81
	s_waitcnt lgkmcnt(1)
	v_add_f32_e32 v129, v129, v147
	ds_bpermute_b32 v147, v152, v129
	v_and_b32_e32 v77, 0xffff0000, v81
	s_waitcnt lgkmcnt(1)
	v_add_f32_e32 v146, v146, v153
	ds_bpermute_b32 v153, v152, v146
	v_lshlrev_b32_e32 v80, 16, v83
	s_waitcnt lgkmcnt(1)
	v_add_f32_e32 v129, v129, v147
	ds_bpermute_b32 v147, v172, v129
	v_and_b32_e32 v81, 0xffff0000, v83
	s_waitcnt lgkmcnt(1)
	v_add_f32_e32 v146, v146, v153
	ds_bpermute_b32 v153, v172, v146
	v_lshlrev_b32_e32 v78, 16, v82
	s_waitcnt lgkmcnt(1)
	v_add_f32_e32 v129, v129, v147
	v_fmamk_f32 v129, v129, 0x3a000000, v127
	v_mul_f32_e32 v147, 0x4f800000, v129
	v_cmp_gt_f32_e32 vcc, s13, v129
	s_waitcnt lgkmcnt(0)
	v_add_f32_e32 v146, v146, v153
	v_fmamk_f32 v146, v146, 0x3a000000, v127
	v_cndmask_b32_e32 v129, v129, v147, vcc
	v_sqrt_f32_e32 v147, v129
	v_mul_f32_e32 v153, 0x4f800000, v146
	v_cmp_gt_f32_e64 s[0:1], s13, v146
	v_and_b32_e32 v79, 0xffff0000, v82
	v_add_u32_e32 v168, -1, v147
	v_cndmask_b32_e64 v146, v146, v153, s[0:1]
	v_sqrt_f32_e32 v153, v146
	v_add_u32_e32 v169, 1, v147
	v_fma_f32 v173, -v168, v147, v129
	v_fma_f32 v188, -v169, v147, v129
	v_cmp_ge_f32_e64 s[2:3], 0, v173
	v_add_u32_e32 v173, 1, v153
	v_lshlrev_b32_e32 v82, 16, v84
	v_cndmask_b32_e64 v147, v147, v168, s[2:3]
	v_add_u32_e32 v168, -1, v153
	v_cmp_lt_f32_e64 s[2:3], 0, v188
	v_fma_f32 v188, -v173, v153, v146
	v_and_b32_e32 v83, 0xffff0000, v84
	v_cndmask_b32_e64 v147, v147, v169, s[2:3]
	v_fma_f32 v169, -v168, v153, v146
	v_cmp_ge_f32_e64 s[2:3], 0, v169
	v_mul_f32_e32 v189, 0x37800000, v147
	v_cndmask_b32_e32 v147, v147, v189, vcc
	v_cndmask_b32_e64 v153, v153, v168, s[2:3]
	v_cmp_lt_f32_e64 s[2:3], 0, v188
	v_cmp_class_f32_e32 vcc, v129, v128
	v_lshlrev_b32_e32 v84, 16, v85
	v_cndmask_b32_e64 v153, v153, v173, s[2:3]
	v_cndmask_b32_e32 v129, v147, v129, vcc
	v_mul_f32_e32 v147, 0x37800000, v153
	v_div_scale_f32 v168, s[2:3], v129, v129, 1.0
	v_cndmask_b32_e64 v147, v153, v147, s[0:1]
	v_cmp_class_f32_e64 s[0:1], v146, v128
	v_rcp_f32_e32 v153, v168
	v_div_scale_f32 v169, vcc, 1.0, v129, 1.0
	v_cndmask_b32_e64 v173, v147, v146, s[0:1]
	v_div_scale_f32 v147, s[0:1], v173, v173, 1.0
	v_rcp_f32_e32 v189, v147
	v_fma_f32 v146, -v168, v153, 1.0
	v_fmac_f32_e32 v153, v146, v153
	v_mul_f32_e32 v146, v169, v153
	v_fma_f32 v192, -v147, v189, 1.0
	v_div_scale_f32 v188, s[0:1], 1.0, v173, 1.0
	v_fma_f32 v193, -v168, v146, v169
	v_fmac_f32_e32 v189, v192, v189
	v_fmac_f32_e32 v146, v193, v153
	v_mul_f32_e32 v192, v188, v189
	v_fma_f32 v168, -v168, v146, v169
	v_fma_f32 v169, -v147, v192, v188
	v_div_fmas_f32 v146, v168, v153, v146
	v_fmac_f32_e32 v192, v169, v189
	v_div_fixup_f32 v146, v146, v129, 1.0
	v_fma_f32 v129, -v147, v192, v188
	s_mov_b64 vcc, s[0:1]
	v_pk_mul_f32 v[38:39], v[146:147], v[38:39] op_sel_hi:[0,1]
	v_pk_mul_f32 v[48:49], v[146:147], v[48:49] op_sel_hi:[0,1]
	v_pk_mul_f32 v[56:57], v[146:147], v[56:57] op_sel_hi:[0,1]
	v_div_fmas_f32 v129, v129, v189, v192
	v_pk_mul_f32 v[50:51], v[146:147], v[50:51] op_sel_hi:[0,1]
	v_pk_mul_f32 v[52:53], v[146:147], v[52:53] op_sel_hi:[0,1]
	v_pk_mul_f32 v[54:55], v[146:147], v[54:55] op_sel_hi:[0,1]
	v_pk_mul_f32 v[58:59], v[146:147], v[58:59] op_sel_hi:[0,1]
	v_pk_mul_f32 v[60:61], v[146:147], v[60:61] op_sel_hi:[0,1]
	v_pk_mul_f32 v[62:63], v[146:147], v[62:63] op_sel_hi:[0,1]
	v_pk_mul_f32 v[64:65], v[146:147], v[64:65] op_sel_hi:[0,1]
	v_pk_mul_f32 v[68:69], v[146:147], v[68:69] op_sel_hi:[0,1]
	v_pk_mul_f32 v[72:73], v[146:147], v[72:73] op_sel_hi:[0,1]
	v_pk_mul_f32 v[102:103], v[146:147], v[102:103] op_sel_hi:[0,1]
	v_pk_mul_f32 v[104:105], v[146:147], v[104:105] op_sel_hi:[0,1]
	v_pk_mul_f32 v[166:167], v[146:147], v[166:167] op_sel_hi:[0,1]
	v_pk_mul_f32 v[106:107], v[146:147], v[106:107] op_sel_hi:[0,1]
; __device__ __forceinline__ float bf_lo(unsigned w) { return __uint_as_float(w << 16); }
; __device__ __forceinline__ float bf_hi(unsigned w) { return __uint_as_float(w & 0xffff0000u); }
; __global__ void __launch_bounds__(NWAVES * 64, 2) hymba_fwd(Args a) {
;     ...
;             for (int q = 0; q < 2; ++q) {
;                 const float rf = 1.0f / sqrtf(wave_sum(sf[q]) * (1.0f / DM) + RMS_EPS), rx = rhi[q]; f32x4* ho = (f32x4*)(a.out + (size_t)(mb + q) * DM);
; #pragma unroll
;                 for (int j = 0; j < 4; ++j) {
;                     const f32x4 g0 = gq[2 * j], g1 = gq[2 * j + 1]; const v4u fj = fv[q][j], hj = hv[q][j]; f32x4 h0, h1;
;                     h0.x = bf_lo(hj.x) * rx + bf_lo(fj.x) * rf * g0.x; h0.y = bf_hi(hj.x) * rx + bf_hi(fj.x) * rf * g0.y; h0.z = bf_lo(hj.y) * rx + bf_lo(fj.y) * rf * g0.z; h0.w = bf_hi(hj.y) * rx + bf_hi(fj.y) * rf * g0.w;
;                     h1.x = bf_lo(hj.z) * rx + bf_lo(fj.z) * rf * g1.x; h1.y = bf_hi(hj.z) * rx + bf_hi(fj.z) * rf * g1.y; h1.z = bf_lo(hj.w) * rx + bf_lo(fj.w) * rf * g1.z; h1.w = bf_hi(hj.w) * rx + bf_hi(fj.w) * rf * g1.w;
;                     ho[128 * j + 2 * lane] = h0; ho[128 * j + 2 * lane + 1] = h1;
;                 }
	v_pk_mul_f32 v[38:39], v[2:3], v[38:39]
	v_pk_mul_f32 v[146:147], v[4:5], v[48:49]
	v_pk_mul_f32 v[194:195], v[12:13], v[56:57]
	v_div_fixup_f32 v204, v129, v173, 1.0
	v_and_b32_e32 v85, 0xffff0000, v85
	v_lshlrev_b32_e32 v86, 16, v90
	v_and_b32_e32 v87, 0xffff0000, v90
	v_lshlrev_b32_e32 v88, 16, v91
	v_and_b32_e32 v89, 0xffff0000, v91
	v_lshlrev_b32_e32 v90, 16, v92
	v_and_b32_e32 v91, 0xffff0000, v92
	v_lshlrev_b32_e32 v92, 16, v93
	v_and_b32_e32 v93, 0xffff0000, v93
	v_lshlrev_b32_e32 v94, 16, v98
	v_and_b32_e32 v95, 0xffff0000, v98
	v_lshlrev_b32_e32 v96, 16, v99
	v_and_b32_e32 v97, 0xffff0000, v99
	v_lshlrev_b32_e32 v98, 16, v100
	v_and_b32_e32 v99, 0xffff0000, v100
	v_lshlrev_b32_e32 v100, 16, v101
	v_and_b32_e32 v101, 0xffff0000, v101
	v_pk_mul_f32 v[168:169], v[6:7], v[50:51]
	v_pk_mul_f32 v[188:189], v[8:9], v[52:53]
	v_pk_mul_f32 v[192:193], v[10:11], v[54:55]
	v_pk_mul_f32 v[196:197], v[14:15], v[58:59]
	v_pk_mul_f32 v[198:199], v[16:17], v[60:61]
	v_pk_mul_f32 v[200:201], v[18:19], v[62:63]
	v_pk_mul_f32 v[202:203], v[20:21], v[64:65]
	v_pk_mul_f32 v[68:69], v[22:23], v[68:69]
	v_pk_mul_f32 v[72:73], v[24:25], v[72:73]
	v_pk_mul_f32 v[102:103], v[26:27], v[102:103]
	v_pk_mul_f32 v[104:105], v[28:29], v[104:105]
	v_pk_mul_f32 v[166:167], v[30:31], v[166:167]
	v_pk_mul_f32 v[106:107], v[32:33], v[106:107]
	v_pk_fma_f32 v[48:49], v[44:45], v[66:67], v[38:39] op_sel_hi:[0,1,1]
	v_pk_fma_f32 v[50:51], v[44:45], v[70:71], v[146:147] op_sel_hi:[0,1,1]
	v_pk_fma_f32 v[58:59], v[44:45], v[80:81], v[194:195] op_sel_hi:[0,1,1]
	v_pk_mul_f32 v[38:39], v[204:205], v[108:109] op_sel_hi:[0,1]
	v_pk_mul_f32 v[80:81], v[204:205], v[110:111] op_sel_hi:[0,1]
	v_lshlrev_b32_e32 v170, 16, v142
	v_and_b32_e32 v171, 0xffff0000, v142
	v_lshlrev_b32_e32 v142, 16, v143
	v_and_b32_e32 v143, 0xffff0000, v143
	v_pk_fma_f32 v[52:53], v[44:45], v[74:75], v[168:169] op_sel_hi:[0,1,1]
	v_pk_fma_f32 v[54:55], v[44:45], v[76:77], v[188:189] op_sel_hi:[0,1,1]
	v_pk_fma_f32 v[56:57], v[44:45], v[78:79], v[192:193] op_sel_hi:[0,1,1]
	v_pk_fma_f32 v[60:61], v[44:45], v[82:83], v[196:197] op_sel_hi:[0,1,1]
	v_pk_fma_f32 v[62:63], v[44:45], v[84:85], v[198:199] op_sel_hi:[0,1,1]
	v_pk_fma_f32 v[64:65], v[44:45], v[86:87], v[200:201] op_sel_hi:[0,1,1]
	v_pk_fma_f32 v[66:67], v[44:45], v[88:89], v[202:203] op_sel_hi:[0,1,1]
	v_pk_fma_f32 v[68:69], v[44:45], v[90:91], v[68:69] op_sel_hi:[0,1,1]
	v_pk_fma_f32 v[70:71], v[44:45], v[92:93], v[72:73] op_sel_hi:[0,1,1]
	v_pk_fma_f32 v[72:73], v[44:45], v[94:95], v[102:103] op_sel_hi:[0,1,1]
	v_pk_fma_f32 v[74:75], v[44:45], v[96:97], v[104:105] op_sel_hi:[0,1,1]
	v_pk_fma_f32 v[76:77], v[44:45], v[98:99], v[166:167] op_sel_hi:[0,1,1]
	v_pk_fma_f32 v[78:79], v[44:45], v[100:101], v[106:107] op_sel_hi:[0,1,1]
	v_pk_mul_f32 v[82:83], v[204:205], v[112:113] op_sel_hi:[0,1]
	v_pk_mul_f32 v[84:85], v[204:205], v[114:115] op_sel_hi:[0,1]
	v_pk_mul_f32 v[86:87], v[204:205], v[116:117] op_sel_hi:[0,1]
	v_pk_mul_f32 v[88:89], v[204:205], v[118:119] op_sel_hi:[0,1]
	v_pk_mul_f32 v[90:91], v[204:205], v[120:121] op_sel_hi:[0,1]
	v_pk_mul_f32 v[92:93], v[204:205], v[122:123] op_sel_hi:[0,1]
	v_pk_mul_f32 v[94:95], v[204:205], v[124:125] op_sel_hi:[0,1]
	v_pk_mul_f32 v[96:97], v[204:205], v[130:131] op_sel_hi:[0,1]
	v_pk_mul_f32 v[98:99], v[204:205], v[164:165] op_sel_hi:[0,1]
	v_pk_mul_f32 v[100:101], v[204:205], v[132:133] op_sel_hi:[0,1]
	v_pk_mul_f32 v[102:103], v[204:205], v[162:163] op_sel_hi:[0,1]
	v_pk_mul_f32 v[104:105], v[204:205], v[154:155] op_sel_hi:[0,1]
	v_pk_mul_f32 v[106:107], v[204:205], v[190:191] op_sel_hi:[0,1]
	v_pk_mul_f32 v[108:109], v[204:205], v[156:157] op_sel_hi:[0,1]
	global_store_dwordx4 v[36:37], v[48:51], off
	global_store_dwordx4 v[36:37], v[52:55], off offset:16
	global_store_dwordx4 v[36:37], v[56:59], off offset:2048
	global_store_dwordx4 v[36:37], v[60:63], off offset:2064
	global_store_dwordx4 v[42:43], v[64:67], off offset:-4096
	global_store_dwordx4 v[46:47], v[68:71], off offset:16
	global_store_dwordx4 v[46:47], v[72:75], off offset:2048
	global_store_dwordx4 v[46:47], v[76:79], off offset:2064
	v_pk_mul_f32 v[36:37], v[2:3], v[38:39]
	v_pk_mul_f32 v[38:39], v[4:5], v[80:81]
	v_lshlrev_b32_e32 v174, 16, v144
	v_and_b32_e32 v175, 0xffff0000, v144
	v_lshlrev_b32_e32 v144, 16, v145
	v_and_b32_e32 v145, 0xffff0000, v145
	v_lshlrev_b32_e32 v176, 16, v134
	v_and_b32_e32 v177, 0xffff0000, v134
	v_lshlrev_b32_e32 v134, 16, v135
	v_and_b32_e32 v135, 0xffff0000, v135
	v_lshlrev_b32_e32 v178, 16, v136
	v_and_b32_e32 v179, 0xffff0000, v136
	v_lshlrev_b32_e32 v136, 16, v137
	v_and_b32_e32 v137, 0xffff0000, v137
	v_lshlrev_b32_e32 v180, 16, v138
	v_and_b32_e32 v181, 0xffff0000, v138
	v_lshlrev_b32_e32 v138, 16, v139
	v_and_b32_e32 v139, 0xffff0000, v139
	v_lshlrev_b32_e32 v182, 16, v140
	v_and_b32_e32 v183, 0xffff0000, v140
	v_lshlrev_b32_e32 v140, 16, v141
	v_and_b32_e32 v141, 0xffff0000, v141
	s_waitcnt vmcnt(8)
; __device__ __forceinline__ float bf_lo(unsigned w) { return __uint_as_float(w << 16); }
; __device__ __forceinline__ float bf_hi(unsigned w) { return __uint_as_float(w & 0xffff0000u); }
; __global__ void __launch_bounds__(NWAVES * 64, 2) hymba_fwd(Args a) {
;     ...
;             for (int q = 0; q < 2; ++q) {
;                 const float rf = 1.0f / sqrtf(wave_sum(sf[q]) * (1.0f / DM) + RMS_EPS), rx = rhi[q]; f32x4* ho = (f32x4*)(a.out + (size_t)(mb + q) * DM);
; #pragma unroll
;                 for (int j = 0; j < 4; ++j) {
;                     const f32x4 g0 = gq[2 * j], g1 = gq[2 * j + 1]; const v4u fj = fv[q][j], hj = hv[q][j]; f32x4 h0, h1;
;                     h0.x = bf_lo(hj.x) * rx + bf_lo(fj.x) * rf * g0.x; h0.y = bf_hi(hj.x) * rx + bf_hi(fj.x) * rf * g0.y; h0.z = bf_lo(hj.y) * rx + bf_lo(fj.y) * rf * g0.z; h0.w = bf_hi(hj.y) * rx + bf_hi(fj.y) * rf * g0.w;
;                     h1.x = bf_lo(hj.z) * rx + bf_lo(fj.z) * rf * g1.x; h1.y = bf_hi(hj.z) * rx + bf_hi(fj.z) * rf * g1.y; h1.z = bf_lo(hj.w) * rx + bf_lo(fj.w) * rf * g1.z; h1.w = bf_hi(hj.w) * rx + bf_hi(fj.w) * rf * g1.w;
;                     ho[128 * j + 2 * lane] = h0; ho[128 * j + 2 * lane + 1] = h1;
;                 }
	v_lshlrev_b32_e32 v184, 16, v158
	v_and_b32_e32 v185, 0xffff0000, v158
	v_lshlrev_b32_e32 v158, 16, v159
	v_and_b32_e32 v159, 0xffff0000, v159
	v_lshlrev_b32_e32 v186, 16, v160
	v_and_b32_e32 v187, 0xffff0000, v160
	v_lshlrev_b32_e32 v160, 16, v161
	v_and_b32_e32 v161, 0xffff0000, v161
	v_pk_mul_f32 v[46:47], v[6:7], v[82:83]
	v_pk_mul_f32 v[48:49], v[8:9], v[84:85]
	v_pk_mul_f32 v[50:51], v[10:11], v[86:87]
	v_pk_mul_f32 v[52:53], v[12:13], v[88:89]
	v_pk_mul_f32 v[54:55], v[14:15], v[90:91]
	v_pk_mul_f32 v[56:57], v[16:17], v[92:93]
	v_pk_mul_f32 v[58:59], v[18:19], v[94:95]
	v_pk_mul_f32 v[60:61], v[20:21], v[96:97]
	v_pk_mul_f32 v[62:63], v[22:23], v[98:99]
	v_pk_mul_f32 v[64:65], v[24:25], v[100:101]
	v_pk_mul_f32 v[66:67], v[26:27], v[102:103]
	v_pk_mul_f32 v[68:69], v[28:29], v[104:105]
	v_pk_mul_f32 v[70:71], v[30:31], v[106:107]
	v_pk_mul_f32 v[72:73], v[32:33], v[108:109]
	v_pk_fma_f32 v[36:37], v[44:45], v[170:171], v[36:37] op_sel:[1,0,0]
	v_pk_fma_f32 v[38:39], v[44:45], v[142:143], v[38:39] op_sel:[1,0,0]
	v_pk_fma_f32 v[46:47], v[44:45], v[174:175], v[46:47] op_sel:[1,0,0]
	v_pk_fma_f32 v[48:49], v[44:45], v[144:145], v[48:49] op_sel:[1,0,0]
	v_pk_fma_f32 v[50:51], v[44:45], v[176:177], v[50:51] op_sel:[1,0,0]
	v_pk_fma_f32 v[52:53], v[44:45], v[134:135], v[52:53] op_sel:[1,0,0]
	v_pk_fma_f32 v[54:55], v[44:45], v[178:179], v[54:55] op_sel:[1,0,0]
	v_pk_fma_f32 v[56:57], v[44:45], v[136:137], v[56:57] op_sel:[1,0,0]
	v_pk_fma_f32 v[58:59], v[44:45], v[180:181], v[58:59] op_sel:[1,0,0]
	v_pk_fma_f32 v[60:61], v[44:45], v[138:139], v[60:61] op_sel:[1,0,0]
	v_pk_fma_f32 v[62:63], v[44:45], v[182:183], v[62:63] op_sel:[1,0,0]
	v_pk_fma_f32 v[64:65], v[44:45], v[140:141], v[64:65] op_sel:[1,0,0]
	v_pk_fma_f32 v[66:67], v[44:45], v[184:185], v[66:67] op_sel:[1,0,0]
	v_pk_fma_f32 v[68:69], v[44:45], v[158:159], v[68:69] op_sel:[1,0,0]
	v_pk_fma_f32 v[70:71], v[44:45], v[186:187], v[70:71] op_sel:[1,0,0]
	v_pk_fma_f32 v[72:73], v[44:45], v[160:161], v[72:73] op_sel:[1,0,0]
	global_store_dwordx4 v[42:43], v[36:39], off
	global_store_dwordx4 v[42:43], v[46:49], off offset:16
	global_store_dwordx4 v[42:43], v[50:53], off offset:2048
	global_store_dwordx4 v[42:43], v[54:57], off offset:2064
	global_store_dwordx4 v[40:41], v[58:61], off
	global_store_dwordx4 v[40:41], v[62:65], off offset:16
	global_store_dwordx4 v[40:41], v[66:69], off offset:2048
	global_store_dwordx4 v[40:41], v[70:73], off offset:2064
	s_cbranch_scc0 .LBB0_975
	s_endpgm
